# LDS-DMA blocks of the FFN1 and OIN/EIN loops: per-piece LDS/global address steps folded into offset:N immediates (one m0 write per A/B group, lane offsets pre-compensated)
# baseline (speedup 1.0000x reference)
; #define G_TILE(kt_, st_) do { const size_t ko_ = (size_t)(kt_) * 1024; unsigned char* d_ = smem + (st_) * 16384; \
;         _Pragma("unroll") for (int s_ = 0; s_ < 8; ++s_) GLDS16(Abase + (size_t)s_ * ksub + ko_ + voff, d_ + s_ * 1024); \
;         _Pragma("unroll") for (int s_ = 0; s_ < 8; ++s_) GLDS16(Bbase + (size_t)s_ * ksub + ko_ + voff, d_ + 8192 + s_ * 1024); } while (0)
; template <int EPI>
; __device__ __forceinline__ void gemm_tile(const Params& p, int l, const u16* __restrict__ A, int lda, const u16* __restrict__ Bt, int K, int m0, int n0, unsigned char* smem) {
;     ...
;     const unsigned voff = (unsigned)(lane * 16);
;     const size_t ksub = (size_t)(K >> 5) * 1024;
;     const unsigned char* Abase = (const unsigned char*)A + (size_t)(m0 >> 4) * ksub;
;     const unsigned char* Bbase = (const unsigned char*)Bt + (size_t)(n0 >> 4) * ksub;
;     (void)lda;
;     ...
;     const int nk = K >> 5;
;     G_TILE(wid, wid);
.LBB0_269:
	s_lshl_b32 s0, s40, 3
	v_mov_b32_e32 v136, v197
	s_ashr_i32 s1, s0, 31
	s_lshl_b64 s[0:1], s[0:1], 15
	v_ashrrev_i32_e32 v66, 6, v136
	v_lshlrev_b32_e32 v0, 4, v136
	v_and_b32_e32 v0, 0x3f0, v0
	s_lshl_b32 s28, s59, 3
	s_ashr_i32 s29, s28, 31
	s_lshl_b64 s[28:29], s[28:29], 15
	v_and_b32_e32 v252, 32, v136
	v_xor_b32_e32 v252, v252, v0
	v_add_u32_e32 v253, 0x7c00, v252
	v_readfirstlane_b32 s36, v66
	s_add_u32 s30, s76, s0
	s_addc_u32 s31, s77, s1
	s_add_u32 s28, s16, s28
	s_addc_u32 s29, s49, s29
	s_lshl_b32 s1, s36, 16
	s_add_u32 s30, s30, s1
	s_addc_u32 s31, s31, 0
	s_add_u32 s28, s28, s1
	s_addc_u32 s29, s29, 0
	s_lshl_b32 s37, s36, 11
	s_add_i32 s38, s37, 0x2000
	s_mov_b32 s23, 0
.Loin_pro:
	s_add_i32 s1, s23, s37
	s_mov_b32 m0, s1
	s_add_i32 s1, s23, s38
	global_load_lds_dwordx4 v252, s[30:31]
	global_load_lds_dwordx4 v253, s[30:31] offset:1024
	s_mov_b32 m0, s1
	s_add_u32 s30, s30, 0x400
	global_load_lds_dwordx4 v252, s[28:29]
	global_load_lds_dwordx4 v253, s[28:29] offset:1024
	s_addc_u32 s31, s31, 0
	s_add_u32 s28, s28, 0x400
	s_addc_u32 s29, s29, 0
	s_add_i32 s23, s23, 0x4000
	s_cmp_lg_u32 s23, 0x8000
	s_cbranch_scc1 .Loin_pro
	v_ashrrev_i32_e32 v73, 7, v136
	v_and_b32_e32 v72, 15, v136
	v_and_b32_e32 v67, 1, v66
	v_lshlrev_b32_e32 v2, 12, v73
	v_lshlrev_b32_e32 v3, 6, v72
	v_and_b32_e32 v4, 48, v136
	v_and_b32_e32 v5, 8, v136
	v_lshlrev_b32_e32 v5, 2, v5
	v_xor_b32_e32 v4, v4, v5
	v_add3_u32 v75, v2, v3, v4
	v_lshlrev_b32_e32 v2, 12, v67
	v_add3_u32 v74, v2, v3, v4
	s_waitcnt lgkmcnt(0)
	v_mov_b32_e32 v2, 0
	v_mov_b32_e32 v3, v2
	v_mov_b32_e32 v4, v2
	v_mov_b32_e32 v5, v2
	v_mov_b32_e32 v6, v2
	v_mov_b32_e32 v7, v2
	v_mov_b32_e32 v8, v2
	v_mov_b32_e32 v9, v2
	v_mov_b32_e32 v10, v2
	v_mov_b32_e32 v11, v2
	v_mov_b32_e32 v12, v2
	v_mov_b32_e32 v13, v2
	v_mov_b32_e32 v14, v2
	v_mov_b32_e32 v15, v2
	v_mov_b32_e32 v16, v2
	v_mov_b32_e32 v17, v2
	v_mov_b32_e32 v18, v2
	v_mov_b32_e32 v19, v2
	v_mov_b32_e32 v20, v2
	v_mov_b32_e32 v21, v2
	v_mov_b32_e32 v22, v2
	v_mov_b32_e32 v23, v2
	v_mov_b32_e32 v24, v2
	v_mov_b32_e32 v25, v2
	v_mov_b32_e32 v26, v2
	v_mov_b32_e32 v27, v2
	v_mov_b32_e32 v28, v2
	v_mov_b32_e32 v29, v2
	v_mov_b32_e32 v30, v2
	v_mov_b32_e32 v31, v2
	v_mov_b32_e32 v32, v2
	v_mov_b32_e32 v33, v2
	v_mov_b32_e32 v34, v2
	v_mov_b32_e32 v35, v2
	v_mov_b32_e32 v36, v2
	v_mov_b32_e32 v37, v2
	v_mov_b32_e32 v38, v2
	v_mov_b32_e32 v39, v2
	v_mov_b32_e32 v40, v2
	v_mov_b32_e32 v41, v2
	v_mov_b32_e32 v42, v2
	v_mov_b32_e32 v43, v2
	v_mov_b32_e32 v44, v2
	v_mov_b32_e32 v45, v2
	v_mov_b32_e32 v46, v2
	v_mov_b32_e32 v47, v2
	v_mov_b32_e32 v48, v2
	v_mov_b32_e32 v49, v2
	v_mov_b32_e32 v50, v2
	v_mov_b32_e32 v51, v2
	v_mov_b32_e32 v52, v2
	v_mov_b32_e32 v53, v2
	v_mov_b32_e32 v54, v2
	v_mov_b32_e32 v55, v2
	v_mov_b32_e32 v56, v2
	v_mov_b32_e32 v57, v2
	v_mov_b32_e32 v58, v2
	v_mov_b32_e32 v59, v2
	v_mov_b32_e32 v60, v2
	v_mov_b32_e32 v61, v2
	v_mov_b32_e32 v62, v2
	v_mov_b32_e32 v63, v2
	v_mov_b32_e32 v64, v2
	v_mov_b32_e32 v65, v2
	s_mov_b64 s[46:47], 0x6adc100
	s_mov_b64 s[18:19], 0x6ae4100
	s_mov_b64 s[44:45], 0x6aec100
	s_mov_b32 s36, 0
	s_mov_b32 s0, 0
	v_add_u32_e32 v88, s0, v75
	v_add_u32_e32 v104, s0, v74
	s_branch .Loin_head

; #define G_TILE(kt_, st_) do { const size_t ko_ = (size_t)(kt_) * 1024; unsigned char* d_ = smem + (st_) * 16384; \
;         _Pragma("unroll") for (int s_ = 0; s_ < 8; ++s_) GLDS16(Abase + (size_t)s_ * ksub + ko_ + voff, d_ + s_ * 1024); \
;         _Pragma("unroll") for (int s_ = 0; s_ < 8; ++s_) GLDS16(Bbase + (size_t)s_ * ksub + ko_ + voff, d_ + 8192 + s_ * 1024); } while (0)
; template <int EPI>
; __device__ __forceinline__ void gemm_tile(const Params& p, int l, const u16* __restrict__ A, int lda, const u16* __restrict__ Bt, int K, int m0, int n0, unsigned char* smem) {
;     ...
;     for (int kt = 0; kt < nk; ++kt) {
;         if (((kt + 1) & 3) == wid && kt + 1 < nk) asm volatile("s_waitcnt vmcnt(0)" ::: "memory");
;         __builtin_amdgcn_s_barrier();
;         asm volatile("" ::: "memory");
;         if ((kt & 3) == wid && kt + 4 < nk) G_TILE(kt + 4, stn);
;         const int so = st * 16384;
;         bf16x8 af[4], bv[4];
; #pragma unroll
;         for (int i = 0; i < 4; ++i) af[i] = *(const bf16x8*)(fa + so + i * 1024);
.Loin_bar:
	s_barrier
	ds_read_b128 v[92:95], v104 offset:8192
	ds_read_b128 v[96:99], v104 offset:9216
	ds_read_b128 v[100:103], v104 offset:10240
	ds_read_b128 v[104:107], v104 offset:11264
	ds_read_b128 v[76:79], v88
	ds_read_b128 v[80:83], v88 offset:1024
	ds_read_b128 v[84:87], v88 offset:2048
	ds_read_b128 v[88:91], v88 offset:3072
	s_cmp_lt_u32 s36, 30
	s_cbranch_scc0 .Loin_mm
	s_add_i32 s1, s23, s37
	s_mov_b32 m0, s1
	s_add_i32 s1, s23, s38
	global_load_lds_dwordx4 v252, s[30:31]
	global_load_lds_dwordx4 v253, s[30:31] offset:1024
	s_mov_b32 m0, s1
	s_add_u32 s30, s30, 0x400
	global_load_lds_dwordx4 v252, s[28:29]
	global_load_lds_dwordx4 v253, s[28:29] offset:1024
	s_addc_u32 s31, s31, 0
	s_add_u32 s28, s28, 0x400
	s_addc_u32 s29, s29, 0
	s_add_i32 s23, s23, 0x4000
	s_cmp_eq_u32 s23, 0x14000
	s_cselect_b32 s23, 0, s23

; #define G_TILE(kt_, st_) do { const size_t ko_ = (size_t)(kt_) * 1024; unsigned char* d_ = smem + (st_) * 16384; \
;         _Pragma("unroll") for (int s_ = 0; s_ < 8; ++s_) GLDS16(Abase + (size_t)s_ * ksub + ko_ + voff, d_ + s_ * 1024); \
;         _Pragma("unroll") for (int s_ = 0; s_ < 8; ++s_) GLDS16(Bbase + (size_t)s_ * ksub + ko_ + voff, d_ + 8192 + s_ * 1024); } while (0)
; template <int EPI>
; __device__ __forceinline__ void gemm_tile(const Params& p, int l, const u16* __restrict__ A, int lda, const u16* __restrict__ Bt, int K, int m0, int n0, unsigned char* smem) {
;     ...
;     const unsigned voff = (unsigned)(lane * 16);
;     const size_t ksub = (size_t)(K >> 5) * 1024;
;     const unsigned char* Abase = (const unsigned char*)A + (size_t)(m0 >> 4) * ksub;
;     const unsigned char* Bbase = (const unsigned char*)Bt + (size_t)(n0 >> 4) * ksub;
;     (void)lda;
;     ...
;     const int nk = K >> 5;
;     G_TILE(wid, wid);
.LBB0_473:
	s_lshl_b32 s0, s50, 3
	v_mov_b32_e32 v110, v197
	s_ashr_i32 s1, s0, 31
	s_lshl_b64 s[0:1], s[0:1], 15
	v_ashrrev_i32_e32 v66, 6, v110
	v_lshlrev_b32_e32 v0, 4, v110
	v_and_b32_e32 v0, 0x3f0, v0
	s_lshl_b32 s28, s59, 3
	s_ashr_i32 s29, s28, 31
	s_lshl_b64 s[28:29], s[28:29], 15
	v_and_b32_e32 v252, 32, v110
	v_xor_b32_e32 v252, v252, v0
	v_add_u32_e32 v253, 0x7c00, v252
	v_readfirstlane_b32 s36, v66
	s_add_u32 s30, s76, s0
	s_addc_u32 s31, s77, s1
	s_add_u32 s28, s16, s28
	s_addc_u32 s29, s49, s29
	s_lshl_b32 s1, s36, 16
	s_add_u32 s30, s30, s1
	s_addc_u32 s31, s31, 0
	s_add_u32 s28, s28, s1
	s_addc_u32 s29, s29, 0
	s_lshl_b32 s37, s36, 11
	s_add_i32 s38, s37, 0x2000
	s_mov_b32 s23, 0
.Lein_pro:
	s_add_i32 s1, s23, s37
	s_mov_b32 m0, s1
	s_add_i32 s1, s23, s38
	global_load_lds_dwordx4 v252, s[30:31]
	global_load_lds_dwordx4 v253, s[30:31] offset:1024
	s_mov_b32 m0, s1
	s_add_u32 s30, s30, 0x400
	global_load_lds_dwordx4 v252, s[28:29]
	global_load_lds_dwordx4 v253, s[28:29] offset:1024
	s_addc_u32 s31, s31, 0
	s_add_u32 s28, s28, 0x400
	s_addc_u32 s29, s29, 0
	s_add_i32 s23, s23, 0x4000
	s_cmp_lg_u32 s23, 0x8000
	s_cbranch_scc1 .Lein_pro
	v_ashrrev_i32_e32 v73, 7, v110
	v_and_b32_e32 v72, 15, v110
	v_and_b32_e32 v67, 1, v66
	v_lshlrev_b32_e32 v2, 12, v73
	v_lshlrev_b32_e32 v3, 6, v72
	v_and_b32_e32 v4, 48, v110
	v_and_b32_e32 v5, 8, v110
	v_lshlrev_b32_e32 v5, 2, v5
	v_xor_b32_e32 v4, v4, v5
	v_add3_u32 v75, v2, v3, v4
	v_lshlrev_b32_e32 v2, 12, v67
	v_add3_u32 v74, v2, v3, v4
	s_waitcnt lgkmcnt(0)
	v_mov_b32_e32 v2, 0
	v_mov_b32_e32 v3, v2
	v_mov_b32_e32 v4, v2
	v_mov_b32_e32 v5, v2
	v_mov_b32_e32 v6, v2
	v_mov_b32_e32 v7, v2
	v_mov_b32_e32 v8, v2
	v_mov_b32_e32 v9, v2
	v_mov_b32_e32 v10, v2
	v_mov_b32_e32 v11, v2
	v_mov_b32_e32 v12, v2
	v_mov_b32_e32 v13, v2
	v_mov_b32_e32 v14, v2
	v_mov_b32_e32 v15, v2
	v_mov_b32_e32 v16, v2
	v_mov_b32_e32 v17, v2
	v_mov_b32_e32 v18, v2
	v_mov_b32_e32 v19, v2
	v_mov_b32_e32 v20, v2
	v_mov_b32_e32 v21, v2
	v_mov_b32_e32 v22, v2
	v_mov_b32_e32 v23, v2
	v_mov_b32_e32 v24, v2
	v_mov_b32_e32 v25, v2
	v_mov_b32_e32 v26, v2
	v_mov_b32_e32 v27, v2
	v_mov_b32_e32 v28, v2
	v_mov_b32_e32 v29, v2
	v_mov_b32_e32 v30, v2
	v_mov_b32_e32 v31, v2
	v_mov_b32_e32 v32, v2
	v_mov_b32_e32 v33, v2
	v_mov_b32_e32 v34, v2
	v_mov_b32_e32 v35, v2
	v_mov_b32_e32 v36, v2
	v_mov_b32_e32 v37, v2
	v_mov_b32_e32 v38, v2
	v_mov_b32_e32 v39, v2
	v_mov_b32_e32 v40, v2
	v_mov_b32_e32 v41, v2
	v_mov_b32_e32 v42, v2
	v_mov_b32_e32 v43, v2
	v_mov_b32_e32 v44, v2
	v_mov_b32_e32 v45, v2
	v_mov_b32_e32 v46, v2
	v_mov_b32_e32 v47, v2
	v_mov_b32_e32 v48, v2
	v_mov_b32_e32 v49, v2
	v_mov_b32_e32 v50, v2
	v_mov_b32_e32 v51, v2
	v_mov_b32_e32 v52, v2
	v_mov_b32_e32 v53, v2
	v_mov_b32_e32 v54, v2
	v_mov_b32_e32 v55, v2
	v_mov_b32_e32 v56, v2
	v_mov_b32_e32 v57, v2
	v_mov_b32_e32 v58, v2
	v_mov_b32_e32 v59, v2
	v_mov_b32_e32 v60, v2
	v_mov_b32_e32 v61, v2
	v_mov_b32_e32 v62, v2
	v_mov_b32_e32 v63, v2
	v_mov_b32_e32 v64, v2
	v_mov_b32_e32 v65, v2
	s_mov_b64 s[18:19], 0x6ae4100
	s_mov_b64 s[40:41], 0x6aec100
	s_mov_b32 s36, 0
	s_mov_b32 s0, 0
	v_add_u32_e32 v88, s0, v75
	v_add_u32_e32 v104, s0, v74
	s_branch .Lein_head

; #define G3_TILE(kt_, st_) do { const size_t ko_ = (size_t)(kt_) * 1024; unsigned char* d_ = smem + (st_) * 20480; \
;         _Pragma("unroll") for (int s_ = 0; s_ < 12; ++s_) GLDS16(Abase + (size_t)s_ * ksub + ko_ + voff, d_ + s_ * 1024); \
;         _Pragma("unroll") for (int s_ = 0; s_ < 8; ++s_) GLDS16(Bbase + (size_t)s_ * ksub + ko_ + voff, d_ + 12288 + s_ * 1024); } while (0)
; template <int EPI>
; __device__ __forceinline__ void gemm_tile3(const Params& p, int l, const u16* __restrict__ A, int lda, const u16* __restrict__ Bt, int K, int m0, int n0, unsigned char* smem) {
;     ...
;     const unsigned voff = (unsigned)(lane * 16);
;     const size_t ksub = (size_t)(K >> 5) * 1024;
;     const unsigned char* Abase = (const unsigned char*)A + (size_t)(m0 >> 4) * ksub;
;     const unsigned char* Bbase = (const unsigned char*)Bt + (size_t)(n0 >> 4) * ksub;
;     (void)lda;
;     ...
;     const int nk = K >> 5;
;     if (wid < 3) G3_TILE(wid, wid);
;     const unsigned char* fa = smem + (wr * 6) * 1024 + fr * 64 + fq * 16;
;     const unsigned char* fb = smem + 12288 + (wc * 4) * 1024 + fr * 64 + fq * 16;
;     int st = 0, stn = 3;
.LBB0_895:
	s_mulk_i32 s1, 0xfea0
	s_add_i32 s1, s1, s0
	s_lshl_b32 s0, s1, 4
	s_and_b32 s49, s0, 0xffffff80
	s_mul_i32 s23, s16, 0xc0
	v_mov_b32_e32 v106, v197
	s_ashr_i32 s28, s49, 4
	s_lshr_b32 s84, s23, 4
	v_ashrrev_i32_e32 v98, 6, v106
	v_lshlrev_b32_e32 v0, 4, v106
	s_ashr_i32 s29, s28, 31
	v_and_b32_e32 v0, 0x3f0, v0
	s_lshl_b64 s[0:1], s[84:85], 15
	s_lshl_b64 s[28:29], s[28:29], 15
	v_and_b32_e32 v252, 32, v106
	v_xor_b32_e32 v252, v252, v0
	v_add_u32_e32 v253, 0x7c00, v252
	v_add_u32_e32 v254, 0xf800, v252
	v_readfirstlane_b32 s16, v98
	s_add_u32 s0, s76, s0
	s_addc_u32 s1, s77, s1
	s_add_u32 s30, s39, s28
	s_addc_u32 s31, s40, s29
	s_mul_i32 s17, s16, 0x18000
	s_add_u32 s28, s0, s17
	s_addc_u32 s29, s1, 0
	s_lshl_b32 s17, s16, 16
	s_add_u32 s30, s30, s17
	s_addc_u32 s31, s31, 0
	s_mul_i32 s54, s16, 0xc00
	s_lshl_b32 s0, s16, 11
	s_addk_i32 s0, 0x3000
	s_mov_b32 s51, 0
.Lf1_pro:
	s_add_i32 s17, s51, s54
	s_add_i32 s18, s51, s0
	s_mov_b32 m0, s17
	s_nop 0
	global_load_lds_dwordx4 v252, s[28:29]
	global_load_lds_dwordx4 v253, s[28:29] offset:1024
	global_load_lds_dwordx4 v254, s[28:29] offset:2048
	s_mov_b32 m0, s18
	s_add_u32 s28, s28, 0x400
	global_load_lds_dwordx4 v252, s[30:31]
	global_load_lds_dwordx4 v253, s[30:31] offset:1024
	s_addc_u32 s29, s29, 0
	s_add_u32 s30, s30, 0x400
	s_addc_u32 s31, s31, 0
	s_add_i32 s51, s51, 0x5000
	s_cmp_lg_u32 s51, 0xa000
	s_cbranch_scc1 .Lf1_pro
	v_ashrrev_i32_e32 v99, 7, v106
	s_movk_i32 s17, 0x1800
	v_and_b32_e32 v103, 15, v106
	v_mul_lo_u32 v2, v99, s17
	v_and_b32_e32 v107, 1, v98
	v_lshlrev_b32_e32 v102, 6, v103
	v_and_b32_e32 v3, 48, v106
	v_and_b32_e32 v4, 8, v106
	v_lshlrev_b32_e32 v4, 2, v4
	v_xor_b32_e32 v3, v3, v4
	v_add3_u32 v108, v2, v102, v3
	v_lshlrev_b32_e32 v2, 12, v107
	v_add3_u32 v109, v2, v102, v3
	s_waitcnt lgkmcnt(0)
	v_mov_b32_e32 v2, 0
	v_mov_b32_e32 v3, v2
	v_mov_b32_e32 v4, v2
	v_mov_b32_e32 v5, v2
	v_mov_b32_e32 v6, v2
	v_mov_b32_e32 v7, v2
	v_mov_b32_e32 v8, v2
	v_mov_b32_e32 v9, v2
	v_mov_b32_e32 v10, v2
	v_mov_b32_e32 v11, v2
	v_mov_b32_e32 v12, v2
	v_mov_b32_e32 v13, v2
	v_mov_b32_e32 v14, v2
	v_mov_b32_e32 v15, v2
	v_mov_b32_e32 v16, v2
	v_mov_b32_e32 v17, v2
	v_mov_b32_e32 v22, v2
	v_mov_b32_e32 v23, v2
	v_mov_b32_e32 v24, v2
	v_mov_b32_e32 v25, v2
	v_mov_b32_e32 v18, v2
	v_mov_b32_e32 v19, v2
	v_mov_b32_e32 v20, v2
	v_mov_b32_e32 v21, v2
	v_mov_b32_e32 v26, v2
	v_mov_b32_e32 v27, v2
	v_mov_b32_e32 v28, v2
	v_mov_b32_e32 v29, v2
	v_mov_b32_e32 v30, v2
	v_mov_b32_e32 v31, v2
	v_mov_b32_e32 v32, v2
	v_mov_b32_e32 v33, v2
	v_mov_b32_e32 v38, v2
	v_mov_b32_e32 v39, v2
	v_mov_b32_e32 v40, v2
	v_mov_b32_e32 v41, v2
	v_mov_b32_e32 v34, v2
	v_mov_b32_e32 v35, v2
	v_mov_b32_e32 v36, v2
	v_mov_b32_e32 v37, v2
	v_mov_b32_e32 v42, v2
	v_mov_b32_e32 v43, v2
	v_mov_b32_e32 v44, v2
	v_mov_b32_e32 v45, v2
	v_mov_b32_e32 v46, v2
	v_mov_b32_e32 v47, v2
	v_mov_b32_e32 v48, v2
	v_mov_b32_e32 v49, v2
	v_mov_b32_e32 v54, v2
	v_mov_b32_e32 v55, v2
	v_mov_b32_e32 v56, v2
	v_mov_b32_e32 v57, v2
	v_mov_b32_e32 v50, v2
	v_mov_b32_e32 v51, v2
	v_mov_b32_e32 v52, v2
	v_mov_b32_e32 v53, v2
	v_mov_b32_e32 v58, v2
	v_mov_b32_e32 v59, v2
	v_mov_b32_e32 v60, v2
	v_mov_b32_e32 v61, v2
	v_mov_b32_e32 v62, v2
	v_mov_b32_e32 v63, v2
	v_mov_b32_e32 v64, v2
	v_mov_b32_e32 v65, v2
	v_mov_b32_e32 v70, v2
	v_mov_b32_e32 v71, v2
	v_mov_b32_e32 v72, v2
	v_mov_b32_e32 v73, v2
	v_mov_b32_e32 v66, v2
	v_mov_b32_e32 v67, v2
	v_mov_b32_e32 v68, v2
	v_mov_b32_e32 v69, v2
	v_mov_b32_e32 v74, v2
	v_mov_b32_e32 v75, v2
	v_mov_b32_e32 v76, v2
	v_mov_b32_e32 v77, v2
	v_mov_b32_e32 v78, v2
	v_mov_b32_e32 v79, v2
	v_mov_b32_e32 v80, v2
	v_mov_b32_e32 v81, v2
	v_mov_b32_e32 v82, v2
	v_mov_b32_e32 v83, v2
	v_mov_b32_e32 v84, v2
	v_mov_b32_e32 v85, v2
	v_mov_b32_e32 v86, v2
	v_mov_b32_e32 v87, v2
	v_mov_b32_e32 v88, v2
	v_mov_b32_e32 v89, v2
	v_mov_b32_e32 v90, v2
	v_mov_b32_e32 v91, v2
	v_mov_b32_e32 v92, v2
	v_mov_b32_e32 v93, v2
	v_mov_b32_e32 v94, v2
	v_mov_b32_e32 v95, v2
	v_mov_b32_e32 v96, v2
	v_mov_b32_e32 v97, v2
	s_mov_b32 s16, 0
	s_mov_b32 s50, 0
	v_add_u32_e32 v110, s50, v109
	v_add_u32_e32 v122, 0x3000, v110
	v_add_u32_e32 v0, s50, v108
	s_branch .Lf1_head

; #define G3_TILE(kt_, st_) do { const size_t ko_ = (size_t)(kt_) * 1024; unsigned char* d_ = smem + (st_) * 20480; \
;         _Pragma("unroll") for (int s_ = 0; s_ < 12; ++s_) GLDS16(Abase + (size_t)s_ * ksub + ko_ + voff, d_ + s_ * 1024); \
;         _Pragma("unroll") for (int s_ = 0; s_ < 8; ++s_) GLDS16(Bbase + (size_t)s_ * ksub + ko_ + voff, d_ + 12288 + s_ * 1024); } while (0)
; #define DSR128(dst_, addr_, off_) asm volatile("ds_read_b128 %0, %1 offset:" #off_ : "=v"(dst_) : "v"(addr_))
; template <int EPI>
; __device__ __forceinline__ void gemm_tile3(const Params& p, int l, const u16* __restrict__ A, int lda, const u16* __restrict__ Bt, int K, int m0, int n0, unsigned char* smem) {
;     ...
;     for (int kt = 0; kt < nk; ++kt) {
;         if (((kt + 1) & 3) == wid && kt + 1 < nk) asm volatile("s_waitcnt vmcnt(0)" ::: "memory");
;         __builtin_amdgcn_s_barrier();
;         asm volatile("" ::: "memory");
;         if (((kt + 3) & 3) == wid && kt + 3 < nk) G3_TILE(kt + 3, stn);
;         const int so = st * 20480;
;         bf16x8 af[6], bv[4];
;         {
;             typedef __attribute__((address_space(3))) unsigned char lds_u8;
;             const unsigned la = (unsigned)(uintptr_t)(lds_u8*)(fa + so);
;             const unsigned lb = (unsigned)(uintptr_t)(lds_u8*)(fb + so);
;     ...
;             DSR128(bv[0], lb, 0); DSR128(bv[1], lb, 1024); DSR128(bv[2], lb, 2048); DSR128(bv[3], lb, 3072);
;             DSR128(af[0], la, 0); DSR128(af[1], la, 1024); DSR128(af[2], la, 2048); DSR128(af[3], la, 3072); DSR128(af[4], la, 4096); DSR128(af[5], la, 5120);
.Lf1_bar:
	s_barrier
	ds_read_b128 v[110:113], v122 offset:0
	ds_read_b128 v[114:117], v122 offset:1024
	ds_read_b128 v[118:121], v122 offset:2048
	ds_read_b128 v[122:125], v122 offset:3072
	ds_read_b128 v[126:129], v0 offset:0
	ds_read_b128 v[130:133], v0 offset:1024
	ds_read_b128 v[134:137], v0 offset:2048
	ds_read_b128 v[138:141], v0 offset:3072
	ds_read_b128 v[142:145], v0 offset:4096
	ds_read_b128 v[146:149], v0 offset:5120
	s_cmp_lt_u32 s16, 30
	s_cbranch_scc0 .Lf1_mm
	s_add_i32 s17, s51, s54
	s_add_i32 s18, s51, s0
	s_mov_b32 m0, s17
	s_nop 0
	global_load_lds_dwordx4 v252, s[28:29]
	global_load_lds_dwordx4 v253, s[28:29] offset:1024
	global_load_lds_dwordx4 v254, s[28:29] offset:2048
	s_mov_b32 m0, s18
	s_add_u32 s28, s28, 0x400
	global_load_lds_dwordx4 v252, s[30:31]
	global_load_lds_dwordx4 v253, s[30:31] offset:1024
	s_addc_u32 s29, s29, 0
	s_add_u32 s30, s30, 0x400
	s_addc_u32 s31, s31, 0
	s_add_i32 s51, s51, 0x5000
	s_cmp_eq_u32 s51, 0x14000
	s_cselect_b32 s51, 0, s51
